# dilated attention bias add: the 40 LUT reads land in two alternating spare pairs, one read ahead (were read-wait-add chained)
# baseline (speedup 1.0000x reference)
.LBB0_100:
	v_add_co_u32_e32 v8, vcc, 0x8000, v4
	s_mov_b32 s1, 0x10000
	s_nop 0
	v_addc_co_u32_e32 v9, vcc, 0, v5, vcc
	global_load_dwordx4 v[146:149], v[8:9], off
	v_add_co_u32_e32 v8, vcc, 0xa000, v4
	s_nop 1
	v_addc_co_u32_e32 v9, vcc, 0, v5, vcc
	global_load_dwordx4 v[150:153], v[8:9], off
	v_add_co_u32_e32 v8, vcc, 0xc000, v4
	s_nop 1
	v_addc_co_u32_e32 v9, vcc, 0, v5, vcc
	global_load_dwordx4 v[154:157], v[8:9], off
	v_add_co_u32_e32 v8, vcc, 0xe000, v4
	s_nop 1
	v_addc_co_u32_e32 v9, vcc, 0, v5, vcc
	global_load_dwordx4 v[158:161], v[8:9], off
	v_add_co_u32_e32 v8, vcc, s1, v4
	s_add_i32 s1, 0, 0x18000
	s_nop 0
	v_addc_co_u32_e32 v9, vcc, 0, v5, vcc
	global_load_dwordx4 v[162:165], v[8:9], off
	v_add_co_u32_e32 v8, vcc, 0x12000, v4
	s_cmp_eq_u32 s81, 0
	s_nop 0
	v_addc_co_u32_e32 v9, vcc, 0, v5, vcc
	global_load_dwordx4 v[166:169], v[8:9], off
	v_add_co_u32_e32 v8, vcc, 0x14000, v4
	s_cselect_b64 s[6:7], -1, 0
	s_nop 0
	v_addc_co_u32_e32 v9, vcc, 0, v5, vcc
	v_add_co_u32_e32 v4, vcc, 0x16000, v4
	global_load_dwordx4 v[170:173], v[8:9], off
	s_nop 0
	v_addc_co_u32_e32 v5, vcc, 0, v5, vcc
	global_load_dwordx4 v[174:177], v[4:5], off
	v_lshlrev_b32_e32 v4, 2, v6
	v_and_b32_e32 v4, 12, v4
	v_bfe_u32 v5, v6, 2, 2
	v_or_b32_e32 v8, v4, v5
	v_bitop3_b32 v4, v4, v226, v5 bitop3:0x36
	v_lshl_add_u32 v9, v227, 8, s80
	v_lshl_add_u32 v10, v4, 4, v9
	v_bitop3_b32 v232, v226, v8, 2 bitop3:0x36
	v_lshl_add_u32 v232, v232, 4, v9
	v_bitop3_b32 v236, v226, v8, 4 bitop3:0x36
	v_lshl_add_u32 v236, v236, 4, v9
	v_bitop3_b32 v237, v226, v8, 6 bitop3:0x36
	v_lshl_add_u32 v237, v237, 4, v9
	v_bitop3_b32 v238, v226, v8, 8 bitop3:0x36
	v_lshl_add_u32 v238, v238, 4, v9
	v_bitop3_b32 v239, v226, v8, 10 bitop3:0x36
	v_lshl_add_u32 v239, v239, 4, v9
	v_bitop3_b32 v240, v226, v8, 12 bitop3:0x36
	v_lshl_add_u32 v240, v240, 4, v9
	v_bitop3_b32 v100, v226, v8, 14 bitop3:0x36
	v_lshl_add_u32 v100, v100, 4, v9
	s_and_b64 s[28:29], s[12:13], s[6:7]
	s_and_b64 vcc, exec, s[28:29]
	ds_read_b128 v[4:7], v10
	ds_read_b128 v[244:247], v232
	s_waitcnt vmcnt(15) lgkmcnt(1)
	v_mfma_f32_32x32x16_bf16 v[64:79], v[4:7], v[0:3], 0
	ds_read_b128 v[4:7], v236
	s_waitcnt vmcnt(14) lgkmcnt(1)
	v_mfma_f32_32x32x16_bf16 v[64:79], v[244:247], v[202:205], v[64:79]
	ds_read_b128 v[244:247], v237
	s_waitcnt vmcnt(13) lgkmcnt(1)
	v_mfma_f32_32x32x16_bf16 v[64:79], v[4:7], v[198:201], v[64:79]
	ds_read_b128 v[4:7], v238
	s_waitcnt vmcnt(12) lgkmcnt(1)
	v_mfma_f32_32x32x16_bf16 v[64:79], v[244:247], v[194:197], v[64:79]
	ds_read_b128 v[244:247], v239
	s_waitcnt vmcnt(11) lgkmcnt(1)
	v_mfma_f32_32x32x16_bf16 v[64:79], v[4:7], v[190:193], v[64:79]
	ds_read_b128 v[4:7], v240
	s_waitcnt vmcnt(10) lgkmcnt(1)
	v_mfma_f32_32x32x16_bf16 v[64:79], v[244:247], v[186:189], v[64:79]
	ds_read_b128 v[244:247], v100
	s_waitcnt vmcnt(9) lgkmcnt(1)
	v_mfma_f32_32x32x16_bf16 v[64:79], v[4:7], v[182:185], v[64:79]
	ds_read_b128 v[4:7], v10 offset:8192
	s_waitcnt vmcnt(8) lgkmcnt(1)
	v_mfma_f32_32x32x16_bf16 v[64:79], v[244:247], v[178:181], v[64:79]
	ds_read_b128 v[244:247], v232 offset:8192
	s_waitcnt lgkmcnt(1)
	v_mfma_f32_32x32x16_bf16 v[48:63], v[4:7], v[0:3], 0
	ds_read_b128 v[4:7], v236 offset:8192
	s_waitcnt lgkmcnt(1)
	v_mfma_f32_32x32x16_bf16 v[48:63], v[244:247], v[202:205], v[48:63]
	ds_read_b128 v[244:247], v237 offset:8192
	s_waitcnt lgkmcnt(1)
	v_mfma_f32_32x32x16_bf16 v[48:63], v[4:7], v[198:201], v[48:63]
	ds_read_b128 v[4:7], v238 offset:8192
	s_waitcnt lgkmcnt(1)
	v_mfma_f32_32x32x16_bf16 v[48:63], v[244:247], v[194:197], v[48:63]
	ds_read_b128 v[244:247], v239 offset:8192
	s_waitcnt lgkmcnt(1)
	v_mfma_f32_32x32x16_bf16 v[48:63], v[4:7], v[190:193], v[48:63]
	ds_read_b128 v[4:7], v240 offset:8192
	s_waitcnt lgkmcnt(1)
	v_mfma_f32_32x32x16_bf16 v[48:63], v[244:247], v[186:189], v[48:63]
	ds_read_b128 v[244:247], v100 offset:8192
	s_waitcnt lgkmcnt(1)
	v_mfma_f32_32x32x16_bf16 v[48:63], v[4:7], v[182:185], v[48:63]
	ds_read_b128 v[4:7], v10 offset:16384
	s_waitcnt lgkmcnt(1)
	v_mfma_f32_32x32x16_bf16 v[48:63], v[244:247], v[178:181], v[48:63]
	ds_read_b128 v[244:247], v232 offset:16384
	s_waitcnt lgkmcnt(1)
	v_mfma_f32_32x32x16_bf16 v[32:47], v[4:7], v[0:3], 0
	ds_read_b128 v[4:7], v236 offset:16384
	s_waitcnt lgkmcnt(1)
	v_mfma_f32_32x32x16_bf16 v[32:47], v[244:247], v[202:205], v[32:47]
	ds_read_b128 v[244:247], v237 offset:16384
	s_waitcnt lgkmcnt(1)
	v_mfma_f32_32x32x16_bf16 v[32:47], v[4:7], v[198:201], v[32:47]
	ds_read_b128 v[4:7], v238 offset:16384
	s_waitcnt lgkmcnt(1)
	v_mfma_f32_32x32x16_bf16 v[32:47], v[244:247], v[194:197], v[32:47]
	ds_read_b128 v[244:247], v239 offset:16384
	s_waitcnt lgkmcnt(1)
	v_mfma_f32_32x32x16_bf16 v[32:47], v[4:7], v[190:193], v[32:47]
	ds_read_b128 v[4:7], v240 offset:16384
	s_waitcnt lgkmcnt(1)
	v_mfma_f32_32x32x16_bf16 v[32:47], v[244:247], v[186:189], v[32:47]
	ds_read_b128 v[244:247], v100 offset:16384
	s_waitcnt lgkmcnt(1)
	v_mfma_f32_32x32x16_bf16 v[32:47], v[4:7], v[182:185], v[32:47]
	s_waitcnt lgkmcnt(0)
	v_mfma_f32_32x32x16_bf16 v[32:47], v[244:247], v[178:181], v[32:47]
	ds_read_b128 v[4:7], v10 offset:24576
	s_waitcnt lgkmcnt(0)
	v_mfma_f32_32x32x16_bf16 v[16:31], v[4:7], v[0:3], 0
	ds_read_b128 v[4:7], v232 offset:24576
	ds_read_b128 v[232:235], v232 offset:32768
	s_waitcnt lgkmcnt(1)
	v_mfma_f32_32x32x16_bf16 v[16:31], v[4:7], v[202:205], v[16:31]
	ds_read_b128 v[4:7], v236 offset:24576
	s_waitcnt lgkmcnt(0)
	v_mfma_f32_32x32x16_bf16 v[16:31], v[4:7], v[198:201], v[16:31]
	ds_read_b128 v[4:7], v237 offset:24576
	s_waitcnt lgkmcnt(0)
	v_mfma_f32_32x32x16_bf16 v[16:31], v[4:7], v[194:197], v[16:31]
	ds_read_b128 v[4:7], v238 offset:24576
	s_waitcnt lgkmcnt(0)
	v_mfma_f32_32x32x16_bf16 v[16:31], v[4:7], v[190:193], v[16:31]
	ds_read_b128 v[4:7], v239 offset:24576
	s_waitcnt lgkmcnt(0)
	v_mfma_f32_32x32x16_bf16 v[16:31], v[4:7], v[186:189], v[16:31]
	ds_read_b128 v[4:7], v240 offset:24576
	s_waitcnt lgkmcnt(0)
	v_mfma_f32_32x32x16_bf16 v[16:31], v[4:7], v[182:185], v[16:31]
	ds_read_b128 v[4:7], v100 offset:24576
	s_waitcnt lgkmcnt(0)
	v_mfma_f32_32x32x16_bf16 v[16:31], v[4:7], v[178:181], v[16:31]
	ds_read_b128 v[4:7], v10 offset:32768
	s_waitcnt lgkmcnt(0)
	v_mfma_f32_32x32x16_bf16 v[0:15], v[4:7], v[0:3], 0
	v_mfma_f32_32x32x16_bf16 v[0:15], v[232:235], v[202:205], v[0:15]
	ds_read_b128 v[202:205], v236 offset:32768
	s_waitcnt lgkmcnt(0)
	v_mfma_f32_32x32x16_bf16 v[0:15], v[202:205], v[198:201], v[0:15]
	ds_read_b128 v[198:201], v237 offset:32768
	v_mov_b32_e32 v202, 0xff800000
	s_waitcnt lgkmcnt(0)
	v_mfma_f32_32x32x16_bf16 v[0:15], v[198:201], v[194:197], v[0:15]
	ds_read_b128 v[194:197], v238 offset:32768
	s_waitcnt lgkmcnt(0)
	v_mfma_f32_32x32x16_bf16 v[0:15], v[194:197], v[190:193], v[0:15]
	ds_read_b128 v[190:193], v239 offset:32768
	v_mov_b32_e32 v195, 0xff800000
	v_mov_b32_e32 v194, 0xff800000
	v_mov_b32_e32 v197, 0xff800000
	v_mov_b32_e32 v196, 0xff800000
	s_waitcnt lgkmcnt(0)
	v_mfma_f32_32x32x16_bf16 v[0:15], v[190:193], v[186:189], v[0:15]
	ds_read_b128 v[186:189], v240 offset:32768
	v_mov_b32_e32 v190, 0xff800000
	v_mov_b32_e32 v191, 0xff800000
	v_mov_b32_e32 v193, 0xff800000
	v_mov_b32_e32 v192, 0xff800000
	s_waitcnt lgkmcnt(0)
	v_mfma_f32_32x32x16_bf16 v[0:15], v[186:189], v[182:185], v[0:15]
	ds_read_b128 v[182:185], v100 offset:32768
	v_mov_b32_e32 v100, 0xff800000
	v_mov_b32_e32 v186, 0xff800000
	v_mov_b32_e32 v189, 0xff800000
	v_mov_b32_e32 v188, 0xff800000
	s_waitcnt lgkmcnt(0)
	v_mfma_f32_32x32x16_bf16 v[0:15], v[182:185], v[178:181], v[0:15]
	v_lshlrev_b32_e32 v180, 2, v226
	v_sub_u32_e32 v181, v227, v180
	v_lshl_add_u32 v187, v181, 2, s1
	v_mov_b32_e32 v178, 0xff800000
	v_mov_b32_e32 v182, 0xff800000
	v_mov_b32_e32 v184, 0xff800000
	v_mov_b32_e32 v183, 0xff800000
	v_mov_b32_e32 v185, 0xff800000
	s_cbranch_vccnz .LBB0_102
	ds_read2_b32 v[244:245], v187 offset0:159 offset1:160
	v_cmp_gt_i32_e32 vcc, 2, v181
	s_mov_b32 s1, 0xff800000
	ds_read2_b32 v[246:247], v187 offset0:157 offset1:158
	s_waitcnt lgkmcnt(1)
	v_pk_add_f32 v[64:65], v[64:65], v[244:245] op_sel:[0,1] op_sel_hi:[1,0]
	s_nop 0
	v_cndmask_b32_e32 v100, v220, v65, vcc
	v_cmp_gt_i32_e32 vcc, 1, v181
	s_nop 1
	v_cndmask_b32_e32 v182, v220, v64, vcc
	v_cmp_gt_i32_e32 vcc, 4, v181
	v_max3_f32 v179, v182, s1, v100
	ds_read2_b32 v[244:245], v187 offset0:151 offset1:152
	s_waitcnt lgkmcnt(1)
	v_pk_add_f32 v[64:65], v[66:67], v[246:247] op_sel:[0,1] op_sel_hi:[1,0]
	s_nop 0
	v_cndmask_b32_e32 v183, v220, v65, vcc
	v_cmp_gt_i32_e32 vcc, 3, v181
	s_nop 1
	v_cndmask_b32_e32 v184, v220, v64, vcc
	v_cmp_gt_i32_e32 vcc, 10, v181
	v_max3_f32 v66, v179, v184, v183
	ds_read2_b32 v[246:247], v187 offset0:149 offset1:150
	s_waitcnt lgkmcnt(1)
	v_pk_add_f32 v[64:65], v[68:69], v[244:245] op_sel:[0,1] op_sel_hi:[1,0]
	s_nop 0
	v_cndmask_b32_e32 v185, v220, v65, vcc
	v_cmp_gt_i32_e32 vcc, 9, v181
	s_nop 1
	v_cndmask_b32_e32 v186, v220, v64, vcc
	v_cmp_gt_i32_e32 vcc, 12, v181
	v_max3_f32 v66, v66, v186, v185
	ds_read2_b32 v[244:245], v187 offset0:143 offset1:144
	s_waitcnt lgkmcnt(1)
	v_pk_add_f32 v[64:65], v[70:71], v[246:247] op_sel:[0,1] op_sel_hi:[1,0]
	s_nop 0
	v_cndmask_b32_e32 v188, v220, v65, vcc
	v_cmp_gt_i32_e32 vcc, 11, v181
	s_nop 1
	v_cndmask_b32_e32 v189, v220, v64, vcc
	v_cmp_gt_i32_e32 vcc, 18, v181
	v_max3_f32 v66, v66, v189, v188
	ds_read2_b32 v[246:247], v187 offset0:141 offset1:142
	s_waitcnt lgkmcnt(1)
	v_pk_add_f32 v[64:65], v[72:73], v[244:245] op_sel:[0,1] op_sel_hi:[1,0]
	s_nop 0
	v_cndmask_b32_e32 v191, v220, v65, vcc
	v_cmp_gt_i32_e32 vcc, 17, v181
	s_nop 1
	v_cndmask_b32_e32 v190, v220, v64, vcc
	v_cmp_gt_i32_e32 vcc, 20, v181
	v_max3_f32 v66, v66, v190, v191
	ds_read2_b32 v[244:245], v187 offset0:135 offset1:136
	s_waitcnt lgkmcnt(1)
	v_pk_add_f32 v[64:65], v[74:75], v[246:247] op_sel:[0,1] op_sel_hi:[1,0]
	s_nop 0
	v_cndmask_b32_e32 v192, v220, v65, vcc
	v_cmp_gt_i32_e32 vcc, 19, v181
	s_nop 1
	v_cndmask_b32_e32 v193, v220, v64, vcc
	v_cmp_gt_i32_e32 vcc, 26, v181
	v_max3_f32 v66, v66, v193, v192
	ds_read2_b32 v[246:247], v187 offset0:133 offset1:134
	s_waitcnt lgkmcnt(1)
	v_pk_add_f32 v[64:65], v[76:77], v[244:245] op_sel:[0,1] op_sel_hi:[1,0]
	s_nop 0
	v_cndmask_b32_e32 v194, v220, v65, vcc
	v_cmp_gt_i32_e32 vcc, 25, v181
	s_nop 1
	v_cndmask_b32_e32 v195, v220, v64, vcc
	v_cmp_gt_i32_e32 vcc, 28, v181
	v_max3_f32 v66, v66, v195, v194
	s_waitcnt lgkmcnt(0)
	v_pk_add_f32 v[64:65], v[78:79], v[246:247] op_sel:[0,1] op_sel_hi:[1,0]
	s_nop 0
	v_cndmask_b32_e32 v196, v220, v65, vcc
	v_cmp_gt_i32_e32 vcc, 27, v181
	s_nop 1
	v_cndmask_b32_e32 v197, v220, v64, vcc
	v_max3_f32 v202, v66, v197, v196
.LBB0_102:
	s_and_b64 s[28:29], s[20:21], s[6:7]
	s_and_b64 vcc, exec, s[28:29]
	s_cbranch_vccnz .LBB0_107
	ds_read2_b32 v[244:245], v187 offset0:127 offset1:128
	ds_read2_b32 v[246:247], v187 offset0:125 offset1:126
	s_waitcnt lgkmcnt(1)
	v_pk_add_f32 v[178:179], v[48:49], v[244:245] op_sel:[0,1] op_sel_hi:[1,0]
	v_max3_f32 v64, v202, v178, v179
	ds_read2_b32 v[244:245], v187 offset0:119 offset1:120
	s_waitcnt lgkmcnt(1)
	v_pk_add_f32 v[48:49], v[50:51], v[246:247] op_sel:[0,1] op_sel_hi:[1,0]
	v_max3_f32 v64, v64, v48, v49
	ds_read2_b32 v[246:247], v187 offset0:117 offset1:118
	s_waitcnt lgkmcnt(1)
	v_pk_add_f32 v[50:51], v[52:53], v[244:245] op_sel:[0,1] op_sel_hi:[1,0]
	v_max3_f32 v64, v64, v50, v51
	ds_read2_b32 v[244:245], v187 offset0:111 offset1:112
	s_waitcnt lgkmcnt(1)
	v_pk_add_f32 v[52:53], v[54:55], v[246:247] op_sel:[0,1] op_sel_hi:[1,0]
	v_max3_f32 v64, v64, v52, v53
	ds_read2_b32 v[246:247], v187 offset0:109 offset1:110
	s_waitcnt lgkmcnt(1)
	v_pk_add_f32 v[54:55], v[56:57], v[244:245] op_sel:[0,1] op_sel_hi:[1,0]
	v_max3_f32 v64, v64, v54, v55
	ds_read2_b32 v[244:245], v187 offset0:103 offset1:104
	s_waitcnt lgkmcnt(1)
	v_pk_add_f32 v[56:57], v[58:59], v[246:247] op_sel:[0,1] op_sel_hi:[1,0]
	v_max3_f32 v64, v64, v56, v57
	ds_read2_b32 v[246:247], v187 offset0:101 offset1:102
	s_waitcnt lgkmcnt(1)
	v_pk_add_f32 v[58:59], v[60:61], v[244:245] op_sel:[0,1] op_sel_hi:[1,0]
	v_max3_f32 v64, v64, v58, v59
	s_waitcnt lgkmcnt(0)
	v_pk_add_f32 v[62:63], v[62:63], v[246:247] op_sel:[0,1] op_sel_hi:[1,0]
	s_nop 0
	v_max3_f32 v202, v64, v62, v63
	s_and_b64 s[28:29], s[22:23], s[6:7]
	v_mov_b32_e32 v60, 0xff800000
	s_and_b64 vcc, exec, s[28:29]
	s_cbranch_vccz .LBB0_108

.LBB0_108:
	ds_read2_b32 v[244:245], v187 offset0:95 offset1:96
	ds_read2_b32 v[246:247], v187 offset0:93 offset1:94
	s_waitcnt lgkmcnt(1)
	v_pk_add_f32 v[32:33], v[32:33], v[244:245] op_sel:[0,1] op_sel_hi:[1,0]
	v_max3_f32 v61, v202, v32, v33
	ds_read2_b32 v[244:245], v187 offset0:87 offset1:88
	s_waitcnt lgkmcnt(1)
	v_pk_add_f32 v[34:35], v[34:35], v[246:247] op_sel:[0,1] op_sel_hi:[1,0]
	v_max3_f32 v61, v61, v34, v35
	ds_read2_b32 v[246:247], v187 offset0:85 offset1:86
	s_waitcnt lgkmcnt(1)
	v_pk_add_f32 v[36:37], v[36:37], v[244:245] op_sel:[0,1] op_sel_hi:[1,0]
	v_max3_f32 v61, v61, v36, v37
	ds_read2_b32 v[244:245], v187 offset0:79 offset1:80
	s_waitcnt lgkmcnt(1)
	v_pk_add_f32 v[38:39], v[38:39], v[246:247] op_sel:[0,1] op_sel_hi:[1,0]
	v_max3_f32 v61, v61, v38, v39
	ds_read2_b32 v[246:247], v187 offset0:77 offset1:78
	s_waitcnt lgkmcnt(1)
	v_pk_add_f32 v[40:41], v[40:41], v[244:245] op_sel:[0,1] op_sel_hi:[1,0]
	v_max3_f32 v61, v61, v40, v41
	ds_read2_b32 v[244:245], v187 offset0:71 offset1:72
	s_waitcnt lgkmcnt(1)
	v_pk_add_f32 v[42:43], v[42:43], v[246:247] op_sel:[0,1] op_sel_hi:[1,0]
	v_max3_f32 v61, v61, v42, v43
	ds_read2_b32 v[246:247], v187 offset0:69 offset1:70
	s_waitcnt lgkmcnt(1)
	v_pk_add_f32 v[44:45], v[44:45], v[244:245] op_sel:[0,1] op_sel_hi:[1,0]
	v_max3_f32 v61, v61, v44, v45
	s_waitcnt lgkmcnt(0)
	v_pk_add_f32 v[46:47], v[46:47], v[246:247] op_sel:[0,1] op_sel_hi:[1,0]
	s_nop 0
	v_max3_f32 v202, v61, v46, v47
	s_and_b64 s[28:29], s[24:25], s[6:7]
	s_and_b64 vcc, exec, s[28:29]
	s_cbranch_vccnz .LBB0_105
.LBB0_109:
	ds_read2_b32 v[244:245], v187 offset0:63 offset1:64
	ds_read2_b32 v[246:247], v187 offset0:61 offset1:62
	s_waitcnt lgkmcnt(1)
	v_pk_add_f32 v[60:61], v[16:17], v[244:245] op_sel:[0,1] op_sel_hi:[1,0]
	v_max3_f32 v64, v202, v60, v61
	ds_read2_b32 v[244:245], v187 offset0:55 offset1:56
	s_waitcnt lgkmcnt(1)
	v_pk_add_f32 v[16:17], v[18:19], v[246:247] op_sel:[0,1] op_sel_hi:[1,0]
	v_max3_f32 v64, v64, v16, v17
	ds_read2_b32 v[246:247], v187 offset0:53 offset1:54
	s_waitcnt lgkmcnt(1)
	v_pk_add_f32 v[18:19], v[20:21], v[244:245] op_sel:[0,1] op_sel_hi:[1,0]
	v_max3_f32 v64, v64, v18, v19
	ds_read2_b32 v[244:245], v187 offset0:47 offset1:48
	s_waitcnt lgkmcnt(1)
	v_pk_add_f32 v[20:21], v[22:23], v[246:247] op_sel:[0,1] op_sel_hi:[1,0]
	v_max3_f32 v64, v64, v20, v21
	ds_read2_b32 v[246:247], v187 offset0:45 offset1:46
	s_waitcnt lgkmcnt(1)
	v_pk_add_f32 v[22:23], v[24:25], v[244:245] op_sel:[0,1] op_sel_hi:[1,0]
	v_max3_f32 v64, v64, v22, v23
	ds_read2_b32 v[244:245], v187 offset0:39 offset1:40
	s_waitcnt lgkmcnt(1)
	v_pk_add_f32 v[24:25], v[26:27], v[246:247] op_sel:[0,1] op_sel_hi:[1,0]
	v_max3_f32 v64, v64, v24, v25
	ds_read2_b32 v[246:247], v187 offset0:37 offset1:38
	s_waitcnt lgkmcnt(1)
	v_pk_add_f32 v[26:27], v[28:29], v[244:245] op_sel:[0,1] op_sel_hi:[1,0]
	v_max3_f32 v64, v64, v26, v27
	s_waitcnt lgkmcnt(0)
	v_pk_add_f32 v[28:29], v[30:31], v[246:247] op_sel:[0,1] op_sel_hi:[1,0]
	s_nop 0
	v_max3_f32 v202, v64, v28, v29
	s_and_b64 s[6:7], s[40:41], s[6:7]
	v_mov_b32_e32 v70, 0xff800000
	s_and_b64 vcc, exec, s[6:7]
	s_cbranch_vccnz .LBB0_106
.LBB0_110:
	ds_read2_b32 v[244:245], v187 offset0:31 offset1:32
	v_cmp_lt_i32_e32 vcc, 0, v181
	ds_read2_b32 v[246:247], v187 offset0:29 offset1:30
	s_waitcnt lgkmcnt(1)
	v_pk_add_f32 v[30:31], v[0:1], v[244:245] op_sel:[0,1] op_sel_hi:[1,0]
	s_nop 0
	v_cndmask_b32_e32 v0, v220, v31, vcc
	v_cmp_lt_i32_e32 vcc, -1, v181
	s_nop 1
	v_cndmask_b32_e32 v70, v220, v30, vcc
	v_cmp_lt_i32_e32 vcc, 2, v181
	v_max3_f32 v64, v202, v70, v0
	ds_read2_b32 v[244:245], v187 offset0:23 offset1:24
	s_waitcnt lgkmcnt(1)
	v_pk_add_f32 v[2:3], v[2:3], v[246:247] op_sel:[0,1] op_sel_hi:[1,0]
	s_nop 0
	v_cndmask_b32_e32 v1, v220, v3, vcc
	v_cmp_lt_i32_e32 vcc, 1, v181
	s_nop 1
	v_cndmask_b32_e32 v71, v220, v2, vcc
	v_cmp_lt_i32_e32 vcc, 8, v181
	v_max3_f32 v30, v64, v71, v1
	ds_read2_b32 v[246:247], v187 offset0:21 offset1:22
	s_waitcnt lgkmcnt(1)
	v_pk_add_f32 v[2:3], v[4:5], v[244:245] op_sel:[0,1] op_sel_hi:[1,0]
	s_nop 0
	v_cndmask_b32_e32 v72, v220, v3, vcc
	v_cmp_lt_i32_e32 vcc, 7, v181
	s_nop 1
	v_cndmask_b32_e32 v73, v220, v2, vcc
	v_cmp_lt_i32_e32 vcc, 10, v181
	v_max3_f32 v4, v30, v73, v72
	ds_read2_b32 v[244:245], v187 offset0:15 offset1:16
	s_waitcnt lgkmcnt(1)
	v_pk_add_f32 v[2:3], v[6:7], v[246:247] op_sel:[0,1] op_sel_hi:[1,0]
	s_nop 0
	v_cndmask_b32_e32 v74, v220, v3, vcc
	v_cmp_lt_i32_e32 vcc, 9, v181
	s_nop 1
	v_cndmask_b32_e32 v75, v220, v2, vcc
	v_cmp_lt_i32_e32 vcc, 16, v181
	v_max3_f32 v4, v4, v75, v74
	ds_read2_b32 v[246:247], v187 offset0:13 offset1:14
	s_waitcnt lgkmcnt(1)
	v_pk_add_f32 v[2:3], v[8:9], v[244:245] op_sel:[0,1] op_sel_hi:[1,0]
	s_nop 0
	v_cndmask_b32_e32 v76, v220, v3, vcc
	v_cmp_lt_i32_e32 vcc, 15, v181
	s_nop 1
	v_cndmask_b32_e32 v77, v220, v2, vcc
	v_cmp_lt_i32_e32 vcc, 18, v181
	v_max3_f32 v4, v4, v77, v76
	ds_read2_b32 v[244:245], v187 offset0:7 offset1:8
	s_waitcnt lgkmcnt(1)
	v_pk_add_f32 v[2:3], v[10:11], v[246:247] op_sel:[0,1] op_sel_hi:[1,0]
	s_nop 0
	v_cndmask_b32_e32 v78, v220, v3, vcc
	v_cmp_lt_i32_e32 vcc, 17, v181
	s_nop 1
	v_cndmask_b32_e32 v79, v220, v2, vcc
	v_cmp_lt_i32_e32 vcc, 24, v181
	v_max3_f32 v4, v4, v79, v78
	ds_read2_b32 v[246:247], v187 offset0:5 offset1:6
	s_waitcnt lgkmcnt(1)
	v_pk_add_f32 v[2:3], v[12:13], v[244:245] op_sel:[0,1] op_sel_hi:[1,0]
	s_nop 0
	v_cndmask_b32_e32 v198, v220, v3, vcc
	v_cmp_lt_i32_e32 vcc, 23, v181
	s_nop 1
	v_cndmask_b32_e32 v199, v220, v2, vcc
	v_cmp_lt_i32_e32 vcc, 26, v181
	v_max3_f32 v4, v4, v199, v198
	s_waitcnt lgkmcnt(0)
	v_pk_add_f32 v[2:3], v[14:15], v[246:247] op_sel:[0,1] op_sel_hi:[1,0]
	s_nop 0
	v_cndmask_b32_e32 v200, v220, v3, vcc
	v_cmp_lt_i32_e32 vcc, 25, v181
	s_nop 1
	v_cndmask_b32_e32 v201, v220, v2, vcc
	v_max3_f32 v202, v4, v201, v200
